# mixer loops: DPP row reduce instead of bpermute butterfly, norm-weight loads issued before the barrier, S-update LDS reads prefetched/pipelined, retention decay as register constant
# speedup vs baseline: 1.0356x; 1.0049x over previous
; #define LAS __attribute__((address_space(3)))
; #define MFMA32(a, b, c) __builtin_amdgcn_mfma_f32_32x32x16_bf16((a), (b), (c), 0, 0, 0)
; template <int TYPE> __device__ __forceinline__ void mixer_mfma_unit(const Frame& F, const Params& p, const unsigned char* ws, int b, int h, const float* hgw) {
;     ...
;         for (int ks = 0; ks < 8; ++ks) {
;             const bf16x8 a = *(const LAS bf16x8*)(L + MX_KS + r * 272 + (16 * ks + 8 * hh) * 2), bq = *(const LAS bf16x8*)(L + MX_QS + r * 272 + (16 * ks + 8 * hh) * 2);
;             pt = MFMA32(a, bq, pt);
;             const bf16x8 aq = mx_frag2(L + MX_QS + r * 272 + (32 * (ks >> 1) + 16 * (ks & 1) + 4 * hh) * 2);
;             y = MFMA32(aq, mx_pack(S[ks >> 1], ks & 1), y);
;         }
; #pragma unroll
;         for (int i = 0; i < 16; ++i) { const int srow = (i & 3) + 8 * (i >> 2) + 4 * hh; if (srow > r) pt[i] = 0.f; }
; #pragma unroll
;         for (int ks = 0; ks < 2; ++ks) y = MFMA32(mx_pack(pt, ks), vf[ks], y);
;         __builtin_amdgcn_sched_barrier(0);
; #pragma unroll
;         for (int dt = 0; dt < 4; ++dt) {
; #pragma unroll
;             for (int q4 = 0; q4 < 4; ++q4) { const f32x4 dv = *(const LAS f32x4*)(L + MX_DEC + (32 * dt + 8 * q4 + 4 * hh) * 4);
; #pragma unroll
;                 for (int k = 0; k < 4; ++k) S[dt][4 * q4 + k] *= dv[k]; }
; #pragma unroll
;             for (int ks = 0; ks < 2; ++ks) { const bf16x8 a = mx_frag2(L + MX_KT + (32 * dt + r) * 80 + (16 * ks + 4 * hh) * 2); S[dt] = MFMA32(a, vf[ks], S[dt]); }
;         }
;     ...
;             for (int i = 0; i < 16; ++i) wn[i] = (TYPE == 1) ? hgw[oe0 + i] : 1.f;
.LBB0_362:
	s_or_b64 exec, exec, s[64:65]
	s_mul_i32 s62, s79, 0xbe00
	s_add_i32 s65, s62, 0
	v_add_u32_e32 v130, s65, v173
	v_add_u32_e32 v126, v130, v187
	ds_read_b128 v[64:67], v126 offset:8704
	ds_read_b128 v[68:71], v126
	ds_read_b128 v[72:75], v126 offset:32
	ds_read_b128 v[76:79], v126 offset:8736
	v_add_u32_e32 v144, v130, v164
	v_add_u32_e32 v145, s65, v164
	s_waitcnt lgkmcnt(2)
	v_mfma_f32_32x32x16_bf16 v[80:95], v[64:67], v[68:71], 0
	v_cvt_pk_bf16_f32 v140, v8, v9
	v_cvt_pk_bf16_f32 v141, v10, v11
	v_cvt_pk_bf16_f32 v142, v12, v13
	v_cvt_pk_bf16_f32 v143, v14, v15
	v_cvt_pk_bf16_f32 v154, v16, v17
	v_cvt_pk_bf16_f32 v155, v18, v19
	v_cvt_pk_bf16_f32 v156, v20, v21
	s_waitcnt lgkmcnt(0)
	v_mfma_f32_32x32x16_bf16 v[80:95], v[76:79], v[72:75], v[80:95]
	ds_read_b128 v[64:67], v126 offset:8768
	ds_read_b128 v[68:71], v126 offset:64
	ds_read_b128 v[72:75], v126 offset:8800
	ds_read_b128 v[76:79], v126 offset:96
	v_cvt_pk_bf16_f32 v157, v22, v23
	v_cvt_pk_bf16_f32 v224, v24, v25
	v_cvt_pk_bf16_f32 v225, v26, v27
	v_cvt_pk_bf16_f32 v226, v28, v29
	v_cvt_pk_bf16_f32 v227, v30, v31
	v_cvt_pk_bf16_f32 v232, v32, v33
	s_waitcnt lgkmcnt(2)
	v_mfma_f32_32x32x16_bf16 v[80:95], v[64:67], v[68:71], v[80:95]
	v_cvt_pk_bf16_f32 v233, v34, v35
	v_cvt_pk_bf16_f32 v234, v36, v37
	v_cvt_pk_bf16_f32 v235, v38, v39
	s_lshl_b32 s62, s79, 14
	s_add_i32 s64, s62, 0
	s_add_i32 s64, s64, 0x17c00
	s_waitcnt lgkmcnt(0)
	v_mfma_f32_32x32x16_bf16 v[80:95], v[72:75], v[76:79], v[80:95]
	ds_read_b128 v[64:67], v126 offset:8832
	ds_read_b128 v[68:71], v126 offset:128
	ds_read_b128 v[72:75], v126 offset:8864
	ds_read_b128 v[76:79], v126 offset:160
	s_waitcnt lgkmcnt(2)
	v_mfma_f32_32x32x16_bf16 v[80:95], v[64:67], v[68:71], v[80:95]
	ds_read_b128 v[68:71], v126 offset:8896
	v_cvt_pk_bf16_f32 v64, v0, v1
	v_cvt_pk_bf16_f32 v65, v2, v3
	v_cvt_pk_bf16_f32 v66, v4, v5
	v_cvt_pk_bf16_f32 v67, v6, v7
	s_waitcnt lgkmcnt(1)
	v_mfma_f32_32x32x16_bf16 v[80:95], v[72:75], v[76:79], v[80:95]
	ds_read_b128 v[72:75], v126 offset:192
	ds_read_b128 v[76:79], v126 offset:8928
	ds_read_b128 v[126:129], v126 offset:224
	s_waitcnt lgkmcnt(2)
	v_mfma_f32_32x32x16_bf16 v[80:95], v[68:71], v[72:75], v[80:95]
	ds_read2_b64 v[68:71], v144 offset1:2
	v_add_u32_e32 v72, v145, v186
	v_add_u32_e32 v72, 0x6800, v72
	s_waitcnt lgkmcnt(1)
	v_mfma_f32_32x32x16_bf16 v[80:95], v[76:79], v[126:129], v[80:95]
	ds_read2_b64 v[198:201], v144 offset0:4 offset1:6
	ds_read2_b64 v[216:219], v144 offset0:8 offset1:10
	ds_read2_b64 v[130:133], v72 offset0:128 offset1:130
	ds_read2_b64 v[126:129], v72 offset0:132 offset1:134
	ds_read2_b64 v[220:223], v144 offset0:12 offset1:14
	ds_read2_b64 v[228:231], v144 offset0:16 offset1:18
	ds_read2_b64 v[236:239], v144 offset0:28 offset1:30
	s_nop 4
	v_cndmask_b32_e64 v81, 0, v81, s[12:13]
	s_waitcnt lgkmcnt(7)
	v_mfma_f32_32x32x16_bf16 v[64:79], v[68:71], v[64:67], 0
	v_cndmask_b32_e64 v88, v88, 0, s[26:27]
	v_cndmask_b32_e64 v89, v89, 0, s[28:29]
	v_cndmask_b32_e64 v90, v90, 0, s[30:31]
	v_cndmask_b32_e64 v91, v91, 0, s[34:35]
	v_cndmask_b32_e64 v82, v82, 0, s[14:15]
	v_cndmask_b32_e64 v83, v83, 0, s[16:17]
	v_cndmask_b32_e64 v167, v85, 0, s[20:21]
	s_waitcnt lgkmcnt(6)
	v_mfma_f32_32x32x16_bf16 v[64:79], v[198:201], v[140:143], v[64:79]
	ds_read2_b64 v[140:143], v144 offset0:20 offset1:22
	v_cvt_pk_bf16_f32 v198, v40, v41
	v_cvt_pk_bf16_f32 v199, v42, v43
	v_cvt_pk_bf16_f32 v200, v44, v45
	v_cvt_pk_bf16_f32 v201, v46, v47
	v_cndmask_b32_e64 v215, v86, 0, s[22:23]
	v_cndmask_b32_e64 v87, v87, 0, s[24:25]
	s_waitcnt lgkmcnt(6)
	v_mfma_f32_32x32x16_bf16 v[64:79], v[216:219], v[154:157], v[64:79]
	ds_read2_b64 v[154:157], v144 offset0:24 offset1:26
	v_cvt_pk_bf16_f32 v216, v48, v49
	v_cvt_pk_bf16_f32 v217, v50, v51
	v_cvt_pk_bf16_f32 v218, v52, v53
	v_cvt_pk_bf16_f32 v219, v54, v55
	v_cndmask_b32_e64 v144, v80, 0, s[10:11]
	v_cndmask_b32_e64 v80, v144, v80, s[12:13]
	s_waitcnt lgkmcnt(4)
	v_mfma_f32_32x32x16_bf16 v[64:79], v[220:223], v[224:227], v[64:79]
	v_cvt_pk_bf16_f32 v220, v56, v57
	v_cvt_pk_bf16_f32 v221, v58, v59
	v_cvt_pk_bf16_f32 v222, v60, v61
	v_cvt_pk_bf16_f32 v223, v62, v63
	v_cndmask_b32_e64 v144, v84, 0, s[18:19]
	v_cndmask_b32_e64 v92, v92, 0, s[36:37]
	v_cndmask_b32_e64 v93, v93, 0, s[38:39]
	s_waitcnt lgkmcnt(3)
	v_mfma_f32_32x32x16_bf16 v[64:79], v[228:231], v[232:235], v[64:79]
	v_cndmask_b32_e64 v94, v94, 0, s[40:41]
	v_cndmask_b32_e64 v95, v95, 0, s[42:43]
	v_cvt_pk_bf16_f32 v84, v80, v81
	v_cvt_pk_bf16_f32 v80, v88, v89
	v_cvt_pk_bf16_f32 v81, v90, v91
	v_cvt_pk_bf16_f32 v85, v82, v83
	v_cvt_pk_bf16_f32 v86, v144, v167
	s_waitcnt lgkmcnt(1)
	v_mfma_f32_32x32x16_bf16 v[64:79], v[140:143], v[198:201], v[64:79]
	v_cvt_pk_bf16_f32 v87, v215, v87
	v_cvt_pk_bf16_f32 v82, v92, v93
	v_cvt_pk_bf16_f32 v83, v94, v95
	s_waitcnt lgkmcnt(0)
	v_mfma_f32_32x32x16_bf16 v[64:79], v[154:157], v[216:219], v[64:79]
	v_mfma_f32_32x32x16_bf16 v[64:79], v[236:239], v[220:223], v[64:79]
	global_load_dwordx4 v[216:219], v[146:147], off offset:48
	global_load_dwordx4 v[220:223], v[146:147], off offset:32
	global_load_dwordx4 v[224:227], v[146:147], off offset:16
	global_load_dwordx4 v[228:231], v[146:147], off
	v_add_u32_e32 v144, s65, v187
	v_add_u32_e32 v145, v145, v191
	ds_read_b128 v[88:91], v144 offset:48128
	ds_read_b128 v[92:95], v144 offset:48160
	ds_read_b128 v[140:143], v144 offset:48192
	ds_read_b128 v[154:157], v144 offset:48224
	v_add_u32_e32 v252, 0x4400, v145
	ds_read2_b64 v[198:201], v252 offset1:2
	ds_read2_b64 v[232:235], v252 offset0:4 offset1:6
	ds_read_b128 v[240:243], v144 offset:48256
	ds_read_b128 v[244:247], v144 offset:48288
	ds_read_b128 v[248:251], v144 offset:48320
	ds_read_b128 v[236:239], v144 offset:48352
	s_waitcnt lgkmcnt(6)
; #define LAS __attribute__((address_space(3)))
; #define MFMA32(a, b, c) __builtin_amdgcn_mfma_f32_32x32x16_bf16((a), (b), (c), 0, 0, 0)
; #define MX_BAR() do { asm volatile("s_waitcnt lgkmcnt(0)" ::: "memory"); __builtin_amdgcn_s_barrier(); asm volatile("" ::: "memory"); } while (0)
; __device__ __forceinline__ unsigned short f2bf1(float x) { return (unsigned short)(cvt_pk_bf16(x, x) & 0xffffu); }
; template <int TYPE> __device__ __forceinline__ void mixer_mfma_unit(const Frame& F, const Params& p, const unsigned char* ws, int b, int h, const float* hgw) {
;     ...
;         for (int dt = 0; dt < 4; ++dt) {
; #pragma unroll
;             for (int q4 = 0; q4 < 4; ++q4) { const f32x4 dv = *(const LAS f32x4*)(L + MX_DEC + (32 * dt + 8 * q4 + 4 * hh) * 4);
; #pragma unroll
;                 for (int k = 0; k < 4; ++k) S[dt][4 * q4 + k] *= dv[k]; }
; #pragma unroll
;             for (int ks = 0; ks < 2; ++ks) { const bf16x8 a = mx_frag2(L + MX_KT + (32 * dt + r) * 80 + (16 * ks + 4 * hh) * 2); S[dt] = MFMA32(a, vf[ks], S[dt]); }
;         }
; #pragma unroll
;         for (int i = 0; i < 16; ++i) *(LAS unsigned short*)(YB + (((i & 3) + 8 * (i >> 2) + 4 * hh) * 256 + 32 * w + r) * 2) = f2bf1(y[i]);
;         MX_BAR();
	v_pk_mul_f32 v[0:1], v[0:1], v[88:89]
	v_pk_mul_f32 v[2:3], v[2:3], v[90:91]
	v_pk_mul_f32 v[4:5], v[4:5], v[92:93]
	v_pk_mul_f32 v[6:7], v[6:7], v[94:95]
	v_pk_mul_f32 v[8:9], v[8:9], v[140:141]
	v_pk_mul_f32 v[10:11], v[10:11], v[142:143]
	v_pk_mul_f32 v[12:13], v[12:13], v[154:155]
	v_pk_mul_f32 v[14:15], v[14:15], v[156:157]
	v_add_u32_e32 v252, 0x4e00, v145
	ds_read2_b64 v[88:91], v252 offset1:2
	ds_read2_b64 v[92:95], v252 offset0:4 offset1:6
	v_mfma_f32_32x32x16_bf16 v[64:79], v[84:87], v[130:133], v[64:79]
	s_add_i32 s62, s64, s52
	s_waitcnt lgkmcnt(7)
	v_mfma_f32_32x32x16_bf16 v[0:15], v[198:201], v[130:133], v[0:15]
	s_waitcnt lgkmcnt(6)
	v_mfma_f32_32x32x16_bf16 v[0:15], v[232:235], v[126:129], v[0:15]
	ds_read_b128 v[140:143], v144 offset:48384
	ds_read_b128 v[154:157], v144 offset:48416
	ds_read_b128 v[198:201], v144 offset:48448
	ds_read_b128 v[232:235], v144 offset:48480
	s_waitcnt lgkmcnt(6)
	v_pk_mul_f32 v[16:17], v[16:17], v[240:241]
	v_pk_mul_f32 v[18:19], v[18:19], v[242:243]
	v_pk_mul_f32 v[20:21], v[20:21], v[244:245]
	v_pk_mul_f32 v[22:23], v[22:23], v[246:247]
	v_pk_mul_f32 v[24:25], v[24:25], v[248:249]
	v_pk_mul_f32 v[26:27], v[26:27], v[250:251]
	v_pk_mul_f32 v[28:29], v[28:29], v[236:237]
	v_pk_mul_f32 v[30:31], v[30:31], v[238:239]
	v_add_u32_e32 v252, 0x5800, v145
	ds_read2_b64 v[240:243], v252 offset1:2
	ds_read2_b64 v[244:247], v252 offset0:4 offset1:6
	v_mfma_f32_32x32x16_bf16 v[64:79], v[80:83], v[126:129], v[64:79]
	v_add3_u32 v80, s62, v192, v165
	s_waitcnt lgkmcnt(7)
	v_mfma_f32_32x32x16_bf16 v[16:31], v[88:91], v[130:133], v[16:31]
	s_waitcnt lgkmcnt(6)
	v_mfma_f32_32x32x16_bf16 v[16:31], v[92:95], v[126:129], v[16:31]
	ds_read_b128 v[248:251], v144 offset:48512
	ds_read_b128 v[236:239], v144 offset:48544
	ds_read_b128 v[88:91], v144 offset:48576
	ds_read_b128 v[92:95], v144 offset:48608
	s_waitcnt lgkmcnt(6)
	v_pk_mul_f32 v[32:33], v[32:33], v[140:141]
	v_pk_mul_f32 v[34:35], v[34:35], v[142:143]
	v_pk_mul_f32 v[36:37], v[36:37], v[154:155]
	v_pk_mul_f32 v[38:39], v[38:39], v[156:157]
	v_pk_mul_f32 v[40:41], v[40:41], v[198:199]
	v_pk_mul_f32 v[42:43], v[42:43], v[200:201]
	v_pk_mul_f32 v[44:45], v[44:45], v[232:233]
	v_pk_mul_f32 v[46:47], v[46:47], v[234:235]
	v_add_u32_e32 v252, 0x6200, v145
	ds_read2_b64 v[140:143], v252 offset1:2
	ds_read2_b64 v[154:157], v252 offset0:4 offset1:6
	s_waitcnt lgkmcnt(7)
	v_mfma_f32_32x32x16_bf16 v[32:47], v[240:243], v[130:133], v[32:47]
	s_waitcnt lgkmcnt(6)
	v_mfma_f32_32x32x16_bf16 v[32:47], v[244:247], v[126:129], v[32:47]
	s_waitcnt lgkmcnt(2)
	v_pk_mul_f32 v[48:49], v[48:49], v[248:249]
	v_pk_mul_f32 v[50:51], v[50:51], v[250:251]
	v_pk_mul_f32 v[52:53], v[52:53], v[236:237]
	v_pk_mul_f32 v[54:55], v[54:55], v[238:239]
	v_pk_mul_f32 v[56:57], v[56:57], v[88:89]
	v_pk_mul_f32 v[58:59], v[58:59], v[90:91]
	v_pk_mul_f32 v[60:61], v[60:61], v[92:93]
	v_pk_mul_f32 v[62:63], v[62:63], v[94:95]
	s_waitcnt lgkmcnt(1)
	s_nop 0
	v_mfma_f32_32x32x16_bf16 v[48:63], v[140:143], v[130:133], v[48:63]
	s_waitcnt lgkmcnt(0)
	v_mfma_f32_32x32x16_bf16 v[48:63], v[154:157], v[126:129], v[48:63]
	v_cvt_pk_bf16_f32 v64, v64, s0
	ds_write_b16 v80, v64
	v_cvt_pk_bf16_f32 v64, v65, s0
	ds_write_b16 v80, v64 offset:512
	v_cvt_pk_bf16_f32 v64, v66, s0
	ds_write_b16 v80, v64 offset:1024
	v_cvt_pk_bf16_f32 v64, v67, s0
	ds_write_b16 v80, v64 offset:1536
	v_cvt_pk_bf16_f32 v64, v68, s0
	ds_write_b16 v80, v64 offset:4096
	v_cvt_pk_bf16_f32 v64, v69, s0
	ds_write_b16 v80, v64 offset:4608
	v_cvt_pk_bf16_f32 v64, v70, s0
	ds_write_b16 v80, v64 offset:5120
	v_cvt_pk_bf16_f32 v64, v71, s0
	ds_write_b16 v80, v64 offset:5632
	v_cvt_pk_bf16_f32 v64, v72, s0
	ds_write_b16 v80, v64 offset:8192
	v_cvt_pk_bf16_f32 v64, v73, s0
	ds_write_b16 v80, v64 offset:8704
	v_cvt_pk_bf16_f32 v64, v74, s0
	ds_write_b16 v80, v64 offset:9216
	v_cvt_pk_bf16_f32 v64, v75, s0
	ds_write_b16 v80, v64 offset:9728
	v_cvt_pk_bf16_f32 v64, v76, s0
	ds_write_b16 v80, v64 offset:12288
	v_cvt_pk_bf16_f32 v64, v77, s0
	ds_write_b16 v80, v64 offset:12800
	v_cvt_pk_bf16_f32 v64, v78, s0
	ds_write_b16 v80, v64 offset:13312
	v_cvt_pk_bf16_f32 v64, v79, s0
	ds_write_b16 v80, v64 offset:13824
	s_waitcnt lgkmcnt(0)
	s_barrier
; __device__ __forceinline__ unsigned cvt_pk_bf16(float lo, float hi) { cvt_f32x2_t v = {lo, hi}; cvt_bf16x2_t b = __builtin_convertvector(v, cvt_bf16x2_t); return __builtin_bit_cast(unsigned, b); }
; #define LAS __attribute__((address_space(3)))
; __device__ __forceinline__ float bflo(unsigned w) { return __uint_as_float(w << 16); }
; __device__ __forceinline__ float bfhi(unsigned w) { return __uint_as_float(w & 0xffff0000u); }
; template <int TYPE> __device__ __forceinline__ void mixer_mfma_unit(const Frame& F, const Params& p, const unsigned char* ws, int b, int h, const float* hgw) {
;     ...
;         {
;             const bool valid = ovalid;
;             f32x4 yv[4]; float ss = 0.f;
;             float wn[16];
; #pragma unroll
;             for (int i = 0; i < 16; ++i) wn[i] = (TYPE == 1) ? hgw[oe0 + i] : 1.f;
;             { const u32x4 ya = *(const LAS u32x4*)(YB + (ot * 256 + oe0) * 2), yb = *(const LAS u32x4*)(YB + (ot * 256 + oe0) * 2 + 16);
;               yv[0] = (f32x4){bflo(ya.x), bfhi(ya.x), bflo(ya.y), bfhi(ya.y)}; yv[1] = (f32x4){bflo(ya.z), bfhi(ya.z), bflo(ya.w), bfhi(ya.w)};
;               yv[2] = (f32x4){bflo(yb.x), bfhi(yb.x), bflo(yb.y), bfhi(yb.y)}; yv[3] = (f32x4){bflo(yb.z), bfhi(yb.z), bflo(yb.w), bfhi(yb.w)}; }
; #pragma unroll
;             for (int k = 0; k < 4; ++k) ss += (yv[k].x * yv[k].x + yv[k].y * yv[k].y) + (yv[k].z * yv[k].z + yv[k].w * yv[k].w);
;             ss += __shfl_xor(ss, 1); ss += __shfl_xor(ss, 2); ss += __shfl_xor(ss, 4); ss += __shfl_xor(ss, 8);
;             const float rs = rsqrtf(ss * (1.f / 256.f) + EPS);
;             const unsigned gg[8] = {g0.x, g0.y, g0.z, g0.w, g1.x, g1.y, g1.z, g1.w};
;             unsigned o[8];
; #pragma unroll
;             for (int k = 0; k < 8; ++k) { const float a0 = yv[k >> 1][(k & 1) * 2] * rs * wn[2 * k] * bflo(gg[k]), a1 = yv[k >> 1][(k & 1) * 2 + 1] * rs * wn[2 * k + 1] * bfhi(gg[k]); o[k] = cvt_pk_bf16(a0, a1); }
;             if (valid) { unsigned char* yp = (unsigned char*)ws + ((unsigned)(TYPE == 0 ? WS_YR : WS_YH) + oo); u32x4 o0, o1; o0.x = o[0]; o0.y = o[1]; o0.z = o[2]; o0.w = o[3]; o1.x = o[4]; o1.y = o[5]; o1.z = o[6]; o1.w = o[7];
;                 *(u32x4*)yp = o0; *(u32x4*)(yp + 16) = o1; }
;         }
	v_add3_u32 v68, s64, v189, v190
	ds_read_b128 v[64:67], v68
	ds_read_b128 v[78:81], v68 offset:16
	s_waitcnt lgkmcnt(1)
	v_lshlrev_b32_e32 v68, 16, v64
	v_and_b32_e32 v69, 0xffff0000, v64
	v_lshlrev_b32_e32 v70, 16, v65
	v_and_b32_e32 v71, 0xffff0000, v65
	v_lshlrev_b32_e32 v72, 16, v66
	v_and_b32_e32 v73, 0xffff0000, v66
	v_lshlrev_b32_e32 v74, 16, v67
	v_and_b32_e32 v75, 0xffff0000, v67
	v_pk_mul_f32 v[82:83], v[68:69], v[68:69]
	v_pk_mul_f32 v[84:85], v[70:71], v[70:71]
	v_pk_mul_f32 v[86:87], v[72:73], v[72:73]
	v_pk_mul_f32 v[88:89], v[74:75], v[74:75]
	s_waitcnt lgkmcnt(0)
	v_lshlrev_b32_e32 v76, 16, v78
	v_and_b32_e32 v77, 0xffff0000, v78
	v_lshlrev_b32_e32 v64, 16, v79
	v_and_b32_e32 v65, 0xffff0000, v79
	v_pk_mul_f32 v[90:91], v[76:77], v[76:77]
	v_pk_mul_f32 v[92:93], v[64:65], v[64:65]
	v_lshlrev_b32_e32 v78, 16, v80
	v_and_b32_e32 v79, 0xffff0000, v80
	v_lshlrev_b32_e32 v66, 16, v81
	v_and_b32_e32 v67, 0xffff0000, v81
	v_add_f32_e32 v88, v88, v89
	v_add_f32_e32 v86, v86, v87
	v_add_f32_e32 v84, v84, v85
	v_add_f32_e32 v82, v82, v83
	v_pk_mul_f32 v[94:95], v[78:79], v[78:79]
	v_pk_mul_f32 v[80:81], v[66:67], v[66:67]
	v_add_f32_e32 v86, v86, v88
	v_add_f32_e32 v82, v82, v84
	v_add_f32_e32 v83, v92, v93
	v_add_f32_e32 v84, v90, v91
	v_add_f32_e32 v82, v82, v86
	v_add_f32_e32 v83, v84, v83
	v_add_f32_e32 v80, v80, v81
	v_add_f32_e32 v81, v94, v95
	v_add_f32_e32 v82, v82, v83
	v_add_f32_e32 v80, v81, v80
	v_add_f32_e32 v80, v80, v82
	s_nop 1
	v_add_f32_dpp v80, v80, v80 row_ror:8 row_mask:0xf bank_mask:0xf
	s_nop 1
	v_add_f32_dpp v80, v80, v80 row_ror:4 row_mask:0xf bank_mask:0xf
	s_nop 1
	v_add_f32_dpp v80, v80, v80 row_ror:2 row_mask:0xf bank_mask:0xf
	s_nop 1
	v_add_f32_dpp v80, v80, v80 row_ror:1 row_mask:0xf bank_mask:0xf
	v_mov_b32_e32 v81, 0
	s_and_saveexec_b64 s[64:65], s[96:97]
	s_cbranch_execz .LBB0_339
	s_waitcnt lgkmcnt(0)
	v_add_f32_e32 v80, v80, v81
	v_fmamk_f32 v80, v80, 0x3b800000, v166
	v_cmp_gt_f32_e32 vcc, s33, v80
	v_mul_f32_e32 v81, 0x4b800000, v80
	s_nop 0
	v_cndmask_b32_e32 v80, v80, v81, vcc
	v_rsq_f32_e32 v80, v80
	s_nop 0
	v_mul_f32_e32 v81, 0x45800000, v80
	v_cndmask_b32_e32 v126, v80, v81, vcc
	v_pk_mul_f32 v[66:67], v[126:127], v[66:67] op_sel_hi:[0,1]
	v_pk_mul_f32 v[78:79], v[126:127], v[78:79] op_sel_hi:[0,1]
	v_pk_mul_f32 v[64:65], v[126:127], v[64:65] op_sel_hi:[0,1]
	v_pk_mul_f32 v[76:77], v[126:127], v[76:77] op_sel_hi:[0,1]
	v_pk_mul_f32 v[74:75], v[126:127], v[74:75] op_sel_hi:[0,1]
	v_pk_mul_f32 v[72:73], v[126:127], v[72:73] op_sel_hi:[0,1]
	v_pk_mul_f32 v[70:71], v[126:127], v[70:71] op_sel_hi:[0,1]
	v_pk_mul_f32 v[68:69], v[126:127], v[68:69] op_sel_hi:[0,1]
	s_waitcnt vmcnt(3)
	v_pk_mul_f32 v[66:67], v[66:67], v[218:219]
	v_lshlrev_b32_e32 v82, 16, v125
	v_and_b32_e32 v83, 0xffff0000, v125
	v_pk_mul_f32 v[78:79], v[78:79], v[216:217]
	v_lshlrev_b32_e32 v80, 16, v124
	v_and_b32_e32 v81, 0xffff0000, v124
	v_pk_mul_f32 v[66:67], v[66:67], v[82:83]
	v_pk_mul_f32 v[78:79], v[78:79], v[80:81]
	v_cvt_pk_bf16_f32 v67, v66, v67
	v_cvt_pk_bf16_f32 v66, v78, v79
	s_waitcnt vmcnt(2)
	v_pk_mul_f32 v[64:65], v[64:65], v[222:223]
	v_lshlrev_b32_e32 v78, 16, v123
	v_and_b32_e32 v79, 0xffff0000, v123
	v_pk_mul_f32 v[64:65], v[64:65], v[78:79]
	v_pk_mul_f32 v[76:77], v[76:77], v[220:221]
	v_lshlrev_b32_e32 v78, 16, v122
	v_and_b32_e32 v79, 0xffff0000, v122
	v_pk_mul_f32 v[76:77], v[76:77], v[78:79]
	v_cvt_pk_bf16_f32 v65, v64, v65
	v_cvt_pk_bf16_f32 v64, v76, v77
	s_waitcnt vmcnt(1)
	v_pk_mul_f32 v[74:75], v[74:75], v[226:227]
	v_lshlrev_b32_e32 v76, 16, v121
	v_and_b32_e32 v77, 0xffff0000, v121
	v_pk_mul_f32 v[74:75], v[74:75], v[76:77]
	v_pk_mul_f32 v[72:73], v[72:73], v[224:225]
	v_lshlrev_b32_e32 v76, 16, v120
	v_and_b32_e32 v77, 0xffff0000, v120
	v_pk_mul_f32 v[72:73], v[72:73], v[76:77]
	v_cvt_pk_bf16_f32 v75, v74, v75
	v_cvt_pk_bf16_f32 v74, v72, v73
	s_waitcnt vmcnt(0)
	v_pk_mul_f32 v[70:71], v[70:71], v[230:231]
	v_lshlrev_b32_e32 v72, 16, v119
	v_and_b32_e32 v73, 0xffff0000, v119
	v_pk_mul_f32 v[70:71], v[70:71], v[72:73]
	v_pk_mul_f32 v[68:69], v[68:69], v[228:229]
	v_cvt_pk_bf16_f32 v73, v70, v71
	v_lshlrev_b32_e32 v70, 16, v118
	v_and_b32_e32 v71, 0xffff0000, v118
	v_pk_mul_f32 v[68:69], v[68:69], v[70:71]
	s_nop 0
	v_cvt_pk_bf16_f32 v72, v68, v69
	v_add_u32_e32 v68, 0x34880000, v139
	global_store_dwordx4 v68, v[72:75], s[94:95]
	global_store_dwordx4 v68, v[64:67], s[94:95] offset:16
	s_branch .LBB0_339

; #define LAS __attribute__((address_space(3)))
; #define MFMA32(a, b, c) __builtin_amdgcn_mfma_f32_32x32x16_bf16((a), (b), (c), 0, 0, 0)
; template <int TYPE> __device__ __forceinline__ void mixer_mfma_unit(const Frame& F, const Params& p, const unsigned char* ws, int b, int h, const float* hgw) {
;     ...
;         for (int ks = 0; ks < 8; ++ks) {
;             const bf16x8 a = *(const LAS bf16x8*)(L + MX_KS + r * 272 + (16 * ks + 8 * hh) * 2), bq = *(const LAS bf16x8*)(L + MX_QS + r * 272 + (16 * ks + 8 * hh) * 2);
;             pt = MFMA32(a, bq, pt);
;             const bf16x8 aq = mx_frag2(L + MX_QS + r * 272 + (32 * (ks >> 1) + 16 * (ks & 1) + 4 * hh) * 2);
;             y = MFMA32(aq, mx_pack(S[ks >> 1], ks & 1), y);
;         }
; #pragma unroll
;         for (int i = 0; i < 16; ++i) { const int srow = (i & 3) + 8 * (i >> 2) + 4 * hh; if (srow > r) pt[i] = 0.f; }
; #pragma unroll
;         for (int ks = 0; ks < 2; ++ks) y = MFMA32(mx_pack(pt, ks), vf[ks], y);
;         __builtin_amdgcn_sched_barrier(0);
; #pragma unroll
;         for (int dt = 0; dt < 4; ++dt) {
; #pragma unroll
;             for (int q4 = 0; q4 < 4; ++q4) { const f32x4 dv = *(const LAS f32x4*)(L + MX_DEC + (32 * dt + 8 * q4 + 4 * hh) * 4);
; #pragma unroll
;                 for (int k = 0; k < 4; ++k) S[dt][4 * q4 + k] *= dv[k]; }
; #pragma unroll
;             for (int ks = 0; ks < 2; ++ks) { const bf16x8 a = mx_frag2(L + MX_KT + (32 * dt + r) * 80 + (16 * ks + 4 * hh) * 2); S[dt] = MFMA32(a, vf[ks], S[dt]); }
;         }
.LBB0_389:
	s_or_b64 exec, exec, s[66:67]
	s_mul_i32 s62, s75, 0xbe00
	s_add_i32 s67, s62, 0
	v_add_u32_e32 v142, s67, v173
	v_add_u32_e32 v138, v142, v187
	ds_read_b128 v[64:67], v138 offset:8704
	ds_read_b128 v[68:71], v138
	ds_read_b128 v[72:75], v138 offset:32
	ds_read_b128 v[76:79], v138 offset:8736
	v_add_u32_e32 v198, v142, v164
	v_add_u32_e32 v167, s67, v164
	s_waitcnt lgkmcnt(2)
	v_mfma_f32_32x32x16_bf16 v[80:95], v[64:67], v[68:71], 0
	v_cvt_pk_bf16_f32 v222, v8, v9
	v_cvt_pk_bf16_f32 v223, v10, v11
	v_cvt_pk_bf16_f32 v224, v12, v13
	v_cvt_pk_bf16_f32 v225, v14, v15
	v_cvt_pk_bf16_f32 v226, v16, v17
	v_cvt_pk_bf16_f32 v227, v18, v19
	v_cvt_pk_bf16_f32 v228, v20, v21
	s_waitcnt lgkmcnt(0)
	v_mfma_f32_32x32x16_bf16 v[80:95], v[76:79], v[72:75], v[80:95]
	ds_read_b128 v[64:67], v138 offset:8768
	ds_read_b128 v[68:71], v138 offset:64
	ds_read_b128 v[72:75], v138 offset:8800
	ds_read_b128 v[76:79], v138 offset:96
	v_cvt_pk_bf16_f32 v229, v22, v23
	v_cvt_pk_bf16_f32 v242, v24, v25
	v_cvt_pk_bf16_f32 v243, v26, v27
	v_cvt_pk_bf16_f32 v244, v28, v29
	v_cvt_pk_bf16_f32 v245, v30, v31
	v_cvt_pk_bf16_f32 v250, v32, v33
	s_waitcnt lgkmcnt(2)
	v_mfma_f32_32x32x16_bf16 v[80:95], v[64:67], v[68:71], v[80:95]
	v_cvt_pk_bf16_f32 v251, v34, v35
	v_cvt_pk_bf16_f32 v252, v36, v37
	v_cvt_pk_bf16_f32 v253, v38, v39
	s_lshl_b32 s62, s75, 14
	s_add_i32 s66, s62, 0
	s_add_i32 s66, s66, 0x17c00
	s_waitcnt lgkmcnt(0)
	v_mfma_f32_32x32x16_bf16 v[80:95], v[72:75], v[76:79], v[80:95]
	ds_read_b128 v[64:67], v138 offset:8832
	ds_read_b128 v[68:71], v138 offset:128
	ds_read_b128 v[72:75], v138 offset:8864
	ds_read_b128 v[76:79], v138 offset:160
	s_waitcnt lgkmcnt(2)
	v_mfma_f32_32x32x16_bf16 v[80:95], v[64:67], v[68:71], v[80:95]
	ds_read_b128 v[68:71], v138 offset:8896
	v_cvt_pk_bf16_f32 v64, v0, v1
	v_cvt_pk_bf16_f32 v65, v2, v3
	v_cvt_pk_bf16_f32 v66, v4, v5
	v_cvt_pk_bf16_f32 v67, v6, v7
	s_waitcnt lgkmcnt(1)
	v_mfma_f32_32x32x16_bf16 v[80:95], v[72:75], v[76:79], v[80:95]
	ds_read_b128 v[72:75], v138 offset:192
	ds_read_b128 v[76:79], v138 offset:8928
	ds_read_b128 v[138:141], v138 offset:224
	s_waitcnt lgkmcnt(2)
	v_mfma_f32_32x32x16_bf16 v[80:95], v[68:71], v[72:75], v[80:95]
	ds_read2_b64 v[68:71], v198 offset1:2
	v_add_u32_e32 v72, v167, v186
	v_add_u32_e32 v72, 0x6800, v72
	s_waitcnt lgkmcnt(1)
	v_mfma_f32_32x32x16_bf16 v[80:95], v[76:79], v[138:141], v[80:95]
	ds_read2_b64 v[230:233], v198 offset0:4 offset1:6
	ds_read2_b64 v[234:237], v198 offset0:8 offset1:10
	ds_read2_b64 v[142:145], v72 offset0:128 offset1:130
	ds_read2_b64 v[138:141], v72 offset0:132 offset1:134
	ds_read2_b64 v[238:241], v198 offset0:12 offset1:14
	ds_read2_b64 v[246:249], v198 offset0:16 offset1:18
	s_nop 5
	v_cndmask_b32_e64 v81, 0, v81, s[12:13]
	s_waitcnt lgkmcnt(6)
	v_mfma_f32_32x32x16_bf16 v[64:79], v[68:71], v[64:67], 0
	v_cndmask_b32_e64 v88, v88, 0, s[26:27]
	v_cndmask_b32_e64 v89, v89, 0, s[28:29]
	v_cndmask_b32_e64 v90, v90, 0, s[30:31]
	v_cndmask_b32_e64 v91, v91, 0, s[34:35]
	v_cndmask_b32_e64 v82, v82, 0, s[14:15]
	v_cndmask_b32_e64 v83, v83, 0, s[16:17]
	v_cndmask_b32_e64 v87, v87, 0, s[24:25]
	s_waitcnt lgkmcnt(5)
	v_mfma_f32_32x32x16_bf16 v[64:79], v[230:233], v[222:225], v[64:79]
	ds_read2_b64 v[222:225], v198 offset0:20 offset1:22
	v_cvt_pk_bf16_f32 v230, v40, v41
	v_cvt_pk_bf16_f32 v231, v42, v43
	v_cvt_pk_bf16_f32 v232, v44, v45
	v_cvt_pk_bf16_f32 v233, v46, v47
	v_cndmask_b32_e64 v92, v92, 0, s[36:37]
	v_cndmask_b32_e64 v93, v93, 0, s[38:39]
	s_waitcnt lgkmcnt(5)
	v_mfma_f32_32x32x16_bf16 v[64:79], v[234:237], v[226:229], v[64:79]
	ds_read2_b64 v[226:229], v198 offset0:24 offset1:26
	v_cvt_pk_bf16_f32 v234, v48, v49
	v_cvt_pk_bf16_f32 v235, v50, v51
	v_cvt_pk_bf16_f32 v236, v52, v53
	v_cvt_pk_bf16_f32 v237, v54, v55
	ds_read2_b64 v[198:201], v198 offset0:28 offset1:30
	v_cndmask_b32_e64 v94, v94, 0, s[40:41]
	s_waitcnt lgkmcnt(4)
	v_mfma_f32_32x32x16_bf16 v[64:79], v[238:241], v[242:245], v[64:79]
	v_cvt_pk_bf16_f32 v238, v56, v57
	v_cvt_pk_bf16_f32 v239, v58, v59
	v_cvt_pk_bf16_f32 v240, v60, v61
	v_cvt_pk_bf16_f32 v241, v62, v63
	v_cndmask_b32_e64 v242, v80, 0, s[10:11]
	v_cndmask_b32_e64 v80, v242, v80, s[12:13]
	v_cndmask_b32_e64 v242, v84, 0, s[18:19]
	s_waitcnt lgkmcnt(3)
	v_mfma_f32_32x32x16_bf16 v[64:79], v[246:249], v[250:253], v[64:79]
	v_cndmask_b32_e64 v243, v85, 0, s[20:21]
	v_cndmask_b32_e64 v244, v86, 0, s[22:23]
	v_cndmask_b32_e64 v95, v95, 0, s[42:43]
	v_cvt_pk_bf16_f32 v84, v80, v81
	v_cvt_pk_bf16_f32 v80, v88, v89
	v_cvt_pk_bf16_f32 v81, v90, v91
	v_cvt_pk_bf16_f32 v85, v82, v83
	s_waitcnt lgkmcnt(2)
	v_mfma_f32_32x32x16_bf16 v[64:79], v[222:225], v[230:233], v[64:79]
	v_cvt_pk_bf16_f32 v86, v242, v243
	v_cvt_pk_bf16_f32 v87, v244, v87
	v_cvt_pk_bf16_f32 v82, v92, v93
	v_cvt_pk_bf16_f32 v83, v94, v95
	s_waitcnt lgkmcnt(1)
	v_mfma_f32_32x32x16_bf16 v[64:79], v[226:229], v[234:237], v[64:79]
	s_waitcnt lgkmcnt(0)
	v_mfma_f32_32x32x16_bf16 v[64:79], v[198:201], v[238:241], v[64:79]
	v_add_u32_e32 v167, v167, v191
	v_add_u32_e32 v226, 0x4400, v167
	v_add_u32_e32 v227, 0x4e00, v167
	v_add_u32_e32 v228, 0x5800, v167
	v_add_u32_e32 v229, 0x6200, v167
	ds_read2_b64 v[88:91], v226 offset1:2
	ds_read2_b64 v[92:95], v226 offset0:4 offset1:6
	ds_read2_b64 v[198:201], v227 offset1:2
	ds_read2_b64 v[222:225], v227 offset0:4 offset1:6
	ds_read2_b64 v[230:233], v228 offset1:2
	ds_read2_b64 v[234:237], v228 offset0:4 offset1:6
	ds_read2_b64 v[238:241], v229 offset1:2
	ds_read2_b64 v[246:249], v229 offset0:4 offset1:6
	v_pk_mul_f32 v[0:1], v[0:1], v[218:219] op_sel_hi:[1,0]
	v_pk_mul_f32 v[2:3], v[2:3], v[218:219] op_sel_hi:[1,0]
	v_pk_mul_f32 v[4:5], v[4:5], v[218:219] op_sel_hi:[1,0]
	v_pk_mul_f32 v[6:7], v[6:7], v[218:219] op_sel_hi:[1,0]
	v_pk_mul_f32 v[8:9], v[8:9], v[218:219] op_sel_hi:[1,0]
	v_pk_mul_f32 v[10:11], v[10:11], v[218:219] op_sel_hi:[1,0]
	v_pk_mul_f32 v[12:13], v[12:13], v[218:219] op_sel_hi:[1,0]
	v_pk_mul_f32 v[14:15], v[14:15], v[218:219] op_sel_hi:[1,0]
	v_mfma_f32_32x32x16_bf16 v[64:79], v[84:87], v[142:145], v[64:79]
	s_add_i32 s62, s66, s52
	s_waitcnt lgkmcnt(7)
; #define LAS __attribute__((address_space(3)))
; #define MFMA32(a, b, c) __builtin_amdgcn_mfma_f32_32x32x16_bf16((a), (b), (c), 0, 0, 0)
; #define MX_BAR() do { asm volatile("s_waitcnt lgkmcnt(0)" ::: "memory"); __builtin_amdgcn_s_barrier(); asm volatile("" ::: "memory"); } while (0)
; __device__ __forceinline__ unsigned short f2bf1(float x) { return (unsigned short)(cvt_pk_bf16(x, x) & 0xffffu); }
; template <int TYPE> __device__ __forceinline__ void mixer_mfma_unit(const Frame& F, const Params& p, const unsigned char* ws, int b, int h, const float* hgw) {
;     ...
;         for (int dt = 0; dt < 4; ++dt) {
; #pragma unroll
;             for (int q4 = 0; q4 < 4; ++q4) { const f32x4 dv = *(const LAS f32x4*)(L + MX_DEC + (32 * dt + 8 * q4 + 4 * hh) * 4);
; #pragma unroll
;                 for (int k = 0; k < 4; ++k) S[dt][4 * q4 + k] *= dv[k]; }
; #pragma unroll
;             for (int ks = 0; ks < 2; ++ks) { const bf16x8 a = mx_frag2(L + MX_KT + (32 * dt + r) * 80 + (16 * ks + 4 * hh) * 2); S[dt] = MFMA32(a, vf[ks], S[dt]); }
;         }
; #pragma unroll
;         for (int i = 0; i < 16; ++i) *(LAS unsigned short*)(YB + (((i & 3) + 8 * (i >> 2) + 4 * hh) * 256 + 32 * w + r) * 2) = f2bf1(y[i]);
;         MX_BAR();
	v_mfma_f32_32x32x16_bf16 v[0:15], v[88:91], v[142:145], v[0:15]
	s_waitcnt lgkmcnt(6)
	v_mfma_f32_32x32x16_bf16 v[0:15], v[92:95], v[138:141], v[0:15]
	v_pk_mul_f32 v[16:17], v[16:17], v[218:219] op_sel_hi:[1,0]
	v_pk_mul_f32 v[18:19], v[18:19], v[218:219] op_sel_hi:[1,0]
	v_pk_mul_f32 v[20:21], v[20:21], v[218:219] op_sel_hi:[1,0]
	v_pk_mul_f32 v[22:23], v[22:23], v[218:219] op_sel_hi:[1,0]
	v_pk_mul_f32 v[24:25], v[24:25], v[218:219] op_sel_hi:[1,0]
	v_pk_mul_f32 v[26:27], v[26:27], v[218:219] op_sel_hi:[1,0]
	v_pk_mul_f32 v[28:29], v[28:29], v[218:219] op_sel_hi:[1,0]
	v_pk_mul_f32 v[30:31], v[30:31], v[218:219] op_sel_hi:[1,0]
	v_mfma_f32_32x32x16_bf16 v[64:79], v[80:83], v[138:141], v[64:79]
	v_add3_u32 v80, s62, v192, v165
	s_waitcnt lgkmcnt(5)
	v_mfma_f32_32x32x16_bf16 v[16:31], v[198:201], v[142:145], v[16:31]
	s_waitcnt lgkmcnt(4)
	v_mfma_f32_32x32x16_bf16 v[16:31], v[222:225], v[138:141], v[16:31]
	v_pk_mul_f32 v[32:33], v[32:33], v[218:219] op_sel_hi:[1,0]
	v_pk_mul_f32 v[34:35], v[34:35], v[218:219] op_sel_hi:[1,0]
	v_pk_mul_f32 v[36:37], v[36:37], v[218:219] op_sel_hi:[1,0]
	v_pk_mul_f32 v[38:39], v[38:39], v[218:219] op_sel_hi:[1,0]
	v_pk_mul_f32 v[40:41], v[40:41], v[218:219] op_sel_hi:[1,0]
	v_pk_mul_f32 v[42:43], v[42:43], v[218:219] op_sel_hi:[1,0]
	v_pk_mul_f32 v[44:45], v[44:45], v[218:219] op_sel_hi:[1,0]
	v_pk_mul_f32 v[46:47], v[46:47], v[218:219] op_sel_hi:[1,0]
	s_waitcnt lgkmcnt(3)
	s_nop 0
	v_mfma_f32_32x32x16_bf16 v[32:47], v[230:233], v[142:145], v[32:47]
	s_waitcnt lgkmcnt(2)
	v_mfma_f32_32x32x16_bf16 v[32:47], v[234:237], v[138:141], v[32:47]
	v_pk_mul_f32 v[48:49], v[48:49], v[218:219] op_sel_hi:[1,0]
	v_pk_mul_f32 v[50:51], v[50:51], v[218:219] op_sel_hi:[1,0]
	v_pk_mul_f32 v[52:53], v[52:53], v[218:219] op_sel_hi:[1,0]
	v_pk_mul_f32 v[54:55], v[54:55], v[218:219] op_sel_hi:[1,0]
	v_pk_mul_f32 v[56:57], v[56:57], v[218:219] op_sel_hi:[1,0]
	v_pk_mul_f32 v[58:59], v[58:59], v[218:219] op_sel_hi:[1,0]
	v_pk_mul_f32 v[60:61], v[60:61], v[218:219] op_sel_hi:[1,0]
	v_pk_mul_f32 v[62:63], v[62:63], v[218:219] op_sel_hi:[1,0]
	s_waitcnt lgkmcnt(1)
	s_nop 0
	v_mfma_f32_32x32x16_bf16 v[48:63], v[238:241], v[142:145], v[48:63]
	s_waitcnt lgkmcnt(0)
	v_mfma_f32_32x32x16_bf16 v[48:63], v[246:249], v[138:141], v[48:63]
	v_cvt_pk_bf16_f32 v64, v64, s0
	ds_write_b16 v80, v64
	v_cvt_pk_bf16_f32 v64, v65, s0
	ds_write_b16 v80, v64 offset:512
	v_cvt_pk_bf16_f32 v64, v66, s0
	ds_write_b16 v80, v64 offset:1024
	v_cvt_pk_bf16_f32 v64, v67, s0
	ds_write_b16 v80, v64 offset:1536
	v_cvt_pk_bf16_f32 v64, v68, s0
	ds_write_b16 v80, v64 offset:4096
	v_cvt_pk_bf16_f32 v64, v69, s0
	ds_write_b16 v80, v64 offset:4608
	v_cvt_pk_bf16_f32 v64, v70, s0
	ds_write_b16 v80, v64 offset:5120
	v_cvt_pk_bf16_f32 v64, v71, s0
	ds_write_b16 v80, v64 offset:5632
	v_cvt_pk_bf16_f32 v64, v72, s0
	ds_write_b16 v80, v64 offset:8192
	v_cvt_pk_bf16_f32 v64, v73, s0
	ds_write_b16 v80, v64 offset:8704
	v_cvt_pk_bf16_f32 v64, v74, s0
	ds_write_b16 v80, v64 offset:9216
	v_cvt_pk_bf16_f32 v64, v75, s0
	ds_write_b16 v80, v64 offset:9728
	v_cvt_pk_bf16_f32 v64, v76, s0
	ds_write_b16 v80, v64 offset:12288
	v_cvt_pk_bf16_f32 v64, v77, s0
	ds_write_b16 v80, v64 offset:12800
	v_cvt_pk_bf16_f32 v64, v78, s0
	ds_write_b16 v80, v64 offset:13312
	v_cvt_pk_bf16_f32 v64, v79, s0
	ds_write_b16 v80, v64 offset:13824
	s_waitcnt lgkmcnt(0)
	s_barrier
; __device__ __forceinline__ unsigned cvt_pk_bf16(float lo, float hi) { cvt_f32x2_t v = {lo, hi}; cvt_bf16x2_t b = __builtin_convertvector(v, cvt_bf16x2_t); return __builtin_bit_cast(unsigned, b); }
; #define LAS __attribute__((address_space(3)))
; __device__ __forceinline__ float bflo(unsigned w) { return __uint_as_float(w << 16); }
; __device__ __forceinline__ float bfhi(unsigned w) { return __uint_as_float(w & 0xffff0000u); }
; template <int TYPE> __device__ __forceinline__ void mixer_mfma_unit(const Frame& F, const Params& p, const unsigned char* ws, int b, int h, const float* hgw) {
;     ...
;         {
;             const bool valid = ovalid;
;             f32x4 yv[4]; float ss = 0.f;
;             float wn[16];
; #pragma unroll
;             for (int i = 0; i < 16; ++i) wn[i] = (TYPE == 1) ? hgw[oe0 + i] : 1.f;
;             { const u32x4 ya = *(const LAS u32x4*)(YB + (ot * 256 + oe0) * 2), yb = *(const LAS u32x4*)(YB + (ot * 256 + oe0) * 2 + 16);
;               yv[0] = (f32x4){bflo(ya.x), bfhi(ya.x), bflo(ya.y), bfhi(ya.y)}; yv[1] = (f32x4){bflo(ya.z), bfhi(ya.z), bflo(ya.w), bfhi(ya.w)};
;               yv[2] = (f32x4){bflo(yb.x), bfhi(yb.x), bflo(yb.y), bfhi(yb.y)}; yv[3] = (f32x4){bflo(yb.z), bfhi(yb.z), bflo(yb.w), bfhi(yb.w)}; }
; #pragma unroll
;             for (int k = 0; k < 4; ++k) ss += (yv[k].x * yv[k].x + yv[k].y * yv[k].y) + (yv[k].z * yv[k].z + yv[k].w * yv[k].w);
;             ss += __shfl_xor(ss, 1); ss += __shfl_xor(ss, 2); ss += __shfl_xor(ss, 4); ss += __shfl_xor(ss, 8);
;             const float rs = rsqrtf(ss * (1.f / 256.f) + EPS);
;             const unsigned gg[8] = {g0.x, g0.y, g0.z, g0.w, g1.x, g1.y, g1.z, g1.w};
;             unsigned o[8];
; #pragma unroll
;             for (int k = 0; k < 8; ++k) { const float a0 = yv[k >> 1][(k & 1) * 2] * rs * wn[2 * k] * bflo(gg[k]), a1 = yv[k >> 1][(k & 1) * 2 + 1] * rs * wn[2 * k + 1] * bfhi(gg[k]); o[k] = cvt_pk_bf16(a0, a1); }
;             if (valid) { unsigned char* yp = (unsigned char*)ws + ((unsigned)(TYPE == 0 ? WS_YR : WS_YH) + oo); u32x4 o0, o1; o0.x = o[0]; o0.y = o[1]; o0.z = o[2]; o0.w = o[3]; o1.x = o[4]; o1.y = o[5]; o1.z = o[6]; o1.w = o[7];
;                 *(u32x4*)yp = o0; *(u32x4*)(yp + 16) = o1; }
;         }
	v_add3_u32 v64, s66, v189, v190
	ds_read_b128 v[68:71], v64
	ds_read_b128 v[76:79], v64 offset:16
	s_waitcnt lgkmcnt(1)
	v_lshlrev_b32_e32 v64, 16, v68
	v_and_b32_e32 v65, 0xffff0000, v68
	v_lshlrev_b32_e32 v66, 16, v69
	v_and_b32_e32 v67, 0xffff0000, v69
	v_lshlrev_b32_e32 v68, 16, v70
	v_and_b32_e32 v69, 0xffff0000, v70
	v_lshlrev_b32_e32 v70, 16, v71
	v_and_b32_e32 v71, 0xffff0000, v71
	v_pk_mul_f32 v[80:81], v[64:65], v[64:65]
	v_pk_mul_f32 v[82:83], v[66:67], v[66:67]
	v_pk_mul_f32 v[84:85], v[68:69], v[68:69]
	v_pk_mul_f32 v[86:87], v[70:71], v[70:71]
	s_waitcnt lgkmcnt(0)
	v_lshlrev_b32_e32 v72, 16, v76
	v_and_b32_e32 v73, 0xffff0000, v76
	v_lshlrev_b32_e32 v74, 16, v77
	v_and_b32_e32 v75, 0xffff0000, v77
	v_pk_mul_f32 v[88:89], v[72:73], v[72:73]
	v_pk_mul_f32 v[90:91], v[74:75], v[74:75]
	v_add_f32_e32 v86, v86, v87
	v_add_f32_e32 v84, v84, v85
	v_add_f32_e32 v82, v82, v83
	v_add_f32_e32 v80, v80, v81
	v_lshlrev_b32_e32 v76, 16, v78
	v_and_b32_e32 v77, 0xffff0000, v78
	v_lshlrev_b32_e32 v78, 16, v79
	v_and_b32_e32 v79, 0xffff0000, v79
	v_add_f32_e32 v84, v84, v86
	v_add_f32_e32 v80, v80, v82
	v_add_f32_e32 v81, v90, v91
	v_add_f32_e32 v82, v88, v89
	v_pk_mul_f32 v[92:93], v[76:77], v[76:77]
	v_pk_mul_f32 v[94:95], v[78:79], v[78:79]
	v_add_f32_e32 v80, v80, v84
	v_add_f32_e32 v81, v82, v81
	v_add_f32_e32 v80, v80, v81
	v_add_f32_e32 v81, v94, v95
	v_add_f32_e32 v82, v92, v93
	v_add_f32_e32 v81, v82, v81
	v_add_f32_e32 v80, v81, v80
	s_nop 1
	v_add_f32_dpp v80, v80, v80 row_ror:8 row_mask:0xf bank_mask:0xf
	s_nop 1
	v_add_f32_dpp v80, v80, v80 row_ror:4 row_mask:0xf bank_mask:0xf
	s_nop 1
	v_add_f32_dpp v80, v80, v80 row_ror:2 row_mask:0xf bank_mask:0xf
	s_nop 1
	v_add_f32_dpp v80, v80, v80 row_ror:1 row_mask:0xf bank_mask:0xf
	v_mov_b32_e32 v81, 0
	s_and_saveexec_b64 s[66:67], s[64:65]
	s_cbranch_execz .LBB0_376
	s_waitcnt lgkmcnt(0)
	v_add_f32_e32 v80, v80, v81
	v_fmamk_f32 v80, v80, 0x3b800000, v166
	v_mul_f32_e32 v81, 0x4b800000, v80
	v_cmp_gt_f32_e32 vcc, s33, v80
	s_nop 1
	v_cndmask_b32_e32 v80, v80, v81, vcc
	v_rsq_f32_e32 v82, v80
	s_waitcnt vmcnt(1)
	v_lshlrev_b32_e32 v80, 16, v137
	v_and_b32_e32 v81, 0xffff0000, v137
	v_mul_f32_e32 v83, 0x45800000, v82
	v_cndmask_b32_e32 v82, v82, v83, vcc
	v_pk_mul_f32 v[78:79], v[82:83], v[78:79] op_sel_hi:[0,1]
	v_pk_mul_f32 v[78:79], v[78:79], v[80:81]
	v_pk_mul_f32 v[76:77], v[82:83], v[76:77] op_sel_hi:[0,1]
	v_lshlrev_b32_e32 v80, 16, v136
	v_and_b32_e32 v81, 0xffff0000, v136
	v_pk_mul_f32 v[76:77], v[76:77], v[80:81]
	v_cvt_pk_bf16_f32 v79, v78, v79
	v_cvt_pk_bf16_f32 v78, v76, v77
	v_pk_mul_f32 v[74:75], v[82:83], v[74:75] op_sel_hi:[0,1]
	v_lshlrev_b32_e32 v76, 16, v135
	v_and_b32_e32 v77, 0xffff0000, v135
	v_pk_mul_f32 v[74:75], v[74:75], v[76:77]
	v_pk_mul_f32 v[72:73], v[82:83], v[72:73] op_sel_hi:[0,1]
	v_cvt_pk_bf16_f32 v77, v74, v75
	v_lshlrev_b32_e32 v74, 16, v134
	v_and_b32_e32 v75, 0xffff0000, v134
	v_pk_mul_f32 v[72:73], v[72:73], v[74:75]
	v_pk_mul_f32 v[70:71], v[82:83], v[70:71] op_sel_hi:[0,1]
	v_cvt_pk_bf16_f32 v76, v72, v73
	s_waitcnt vmcnt(0)
	v_lshlrev_b32_e32 v72, 16, v133
	v_and_b32_e32 v73, 0xffff0000, v133
	v_pk_mul_f32 v[70:71], v[70:71], v[72:73]
	v_pk_mul_f32 v[68:69], v[82:83], v[68:69] op_sel_hi:[0,1]
	v_lshlrev_b32_e32 v72, 16, v132
	v_and_b32_e32 v73, 0xffff0000, v132
	v_pk_mul_f32 v[68:69], v[68:69], v[72:73]
	v_cvt_pk_bf16_f32 v71, v70, v71
	v_cvt_pk_bf16_f32 v70, v68, v69
	v_pk_mul_f32 v[66:67], v[82:83], v[66:67] op_sel_hi:[0,1]
	v_lshlrev_b32_e32 v68, 16, v131
	v_and_b32_e32 v69, 0xffff0000, v131
	v_pk_mul_f32 v[66:67], v[66:67], v[68:69]
	v_pk_mul_f32 v[64:65], v[82:83], v[64:65] op_sel_hi:[0,1]
	v_cvt_pk_bf16_f32 v69, v66, v67
	v_lshlrev_b32_e32 v66, 16, v130
	v_and_b32_e32 v67, 0xffff0000, v130
	v_pk_mul_f32 v[64:65], v[64:65], v[66:67]
	s_nop 0
	v_cvt_pk_bf16_f32 v68, v64, v65
	v_add_u32_e32 v64, 0x30780000, v221
	global_store_dwordx4 v64, v[68:71], s[94:95]
	global_store_dwordx4 v64, v[76:79], s[94:95] offset:16
	s_branch .LBB0_376
